# scan stage 2 MFMAs with swapped operands: each lane holds 4 consecutive columns of one row, one 8-byte store per tile instead of four 2-byte stores
# baseline (speedup 1.0000x reference)
.LBB0_557:
	s_bitcmp1_b32 s63, 0
	s_cbranch_scc1 .Lscan_wall
	s_waitcnt vmcnt(2)
	s_branch .Lscan_wdone

.LBB0_604:
.LBB0_605:
	v_mul_lo_u32 v20, v132, s54
	v_add3_u32 v20, 0, v20, v133
	s_barrier
	ds_read_b128 v[60:63], v20 offset:61440
	ds_read_b128 v[56:59], v20 offset:61504
	v_add_u32_e32 v20, s79, v130
	v_add_u32_e32 v111, s66, v20
	v_add_u32_e32 v20, s67, v20
	ds_read_b64_tr_b16 v[132:133], v111 offset:0
	ds_read_b64_tr_b16 v[134:135], v111 offset:576
	ds_read_b64_tr_b16 v[100:101], v111 offset:4608
	ds_read_b64_tr_b16 v[102:103], v111 offset:5184
	ds_read_b64_tr_b16 v[76:77], v20 offset:0
	ds_read_b64_tr_b16 v[78:79], v20 offset:576
	ds_read_b64_tr_b16 v[72:73], v20 offset:4608
	ds_read_b64_tr_b16 v[74:75], v20 offset:5184
	ds_read_b64_tr_b16 v[68:69], v20 offset:9216
	ds_read_b64_tr_b16 v[70:71], v20 offset:9792
	ds_read_b64_tr_b16 v[64:65], v20 offset:13824
	ds_read_b64_tr_b16 v[66:67], v20 offset:14400
	s_waitcnt lgkmcnt(0)
	s_and_b64 vcc, exec, s[10:11]
	v_mfma_f32_16x16x32_bf16 v[76:79], v[76:79], v[16:19], 0
	v_mfma_f32_16x16x32_bf16 v[72:75], v[72:75], v[80:83], v[76:79]
	v_mfma_f32_16x16x32_bf16 v[68:71], v[68:71], v[84:87], v[72:75]
	v_mfma_f32_16x16x32_bf16 v[64:67], v[64:67], v[96:99], v[68:71]
	s_waitcnt lgkmcnt(1)
	v_mfma_f32_16x16x32_bf16 v[68:71], v[132:135], v[60:63], 0
	s_waitcnt lgkmcnt(0)
	v_mfma_f32_16x16x32_bf16 v[68:71], v[100:103], v[56:59], v[68:71]
	s_and_b64 vcc, exec, s[24:25]
	s_cbranch_vccz .Lscan_eA_orig
	s_and_b64 vcc, exec, s[10:11]
	s_cbranch_vccnz .Lscan_eA_ssd
	s_lshl_b64 s[12:13], s[30:31], 1
	s_add_u32 s12, s28, s12
	s_addc_u32 s13, s29, s13
	v_and_b32_e32 v153, 15, v192
	v_or_b32_e32 v153, s72, v153
	v_add_u32_e32 v150, s84, v153
	v_mul_u32_u24_e32 v151, s3, v150
	v_add_u32_e32 v155, s77, v109
	v_lshl_add_u32 v152, v155, 1, v151
	s_nop 3
	v_pk_add_f32 v[196:197], v[64:65], v[68:69]
	v_pk_add_f32 v[198:199], v[66:67], v[70:71]
	v_cvt_pk_bf16_f32 v196, v196, v197
	v_cvt_pk_bf16_f32 v197, v198, v199
	global_store_dwordx2 v152, v[196:197], s[12:13]
	s_branch .LBB0_647
.Lscan_eA_ssd:
	v_and_b32_e32 v153, 15, v192
	v_or_b32_e32 v153, s72, v153
	v_mul_u32_u24_e32 v154, s54, v153
	v_add_u32_e32 v155, s77, v109
	v_lshl_add_u32 v154, v155, 1, v154
	v_add_u32_e32 v156, s59, v154
	v_add_u32_e32 v157, s64, v154
	ds_read_b64 v[160:161], v156
	ds_read_b64 v[164:165], v157
	v_lshl_add_u32 v158, v153, 2, s71
	ds_read_b32 v158, v158 offset:256
	s_lshl_b64 s[12:13], s[34:35], 1
	s_add_u32 s12, s28, s12
	s_addc_u32 s13, s29, s13
	v_add_u32_e32 v150, s84, v153
	v_mul_u32_u24_e32 v151, s3, v150
	v_lshl_add_u32 v152, v155, 1, v151
	v_mov_b32_e32 v184, v110
	v_mov_b32_e32 v186, v110
	v_mov_b32_e32 v188, v110
	v_mov_b32_e32 v190, v110
	s_waitcnt lgkmcnt(0)
	v_mul_f32_e32 v158, 0x3fb8aa3b, v158
	v_exp_f32_e32 v172, v158
	v_lshlrev_b32_e32 v177, 16, v160
	v_and_b32_e32 v179, 0xffff0000, v160
	v_lshlrev_b32_e32 v181, 16, v161
	v_and_b32_e32 v183, 0xffff0000, v161
	v_mul_f32_e32 v160, 0xbfb8aa3b, v177
	v_mul_f32_e32 v161, 0xbfb8aa3b, v179
	v_mul_f32_e32 v162, 0xbfb8aa3b, v181
	v_mul_f32_e32 v163, 0xbfb8aa3b, v183
	v_exp_f32_e32 v160, v160
	v_exp_f32_e32 v161, v161
	v_exp_f32_e32 v162, v162
	v_exp_f32_e32 v163, v163
	v_lshlrev_b32_e32 v176, 16, v164
	v_and_b32_e32 v178, 0xffff0000, v164
	v_lshlrev_b32_e32 v180, 16, v165
	v_and_b32_e32 v182, 0xffff0000, v165
	v_add_f32_e32 v160, 1.0, v160
	v_add_f32_e32 v161, 1.0, v161
	v_add_f32_e32 v162, 1.0, v162
	v_add_f32_e32 v163, 1.0, v163
	v_rcp_f32_e32 v185, v160
	v_rcp_f32_e32 v187, v161
	v_rcp_f32_e32 v189, v162
	v_rcp_f32_e32 v191, v163
	v_fma_f32 v164, v64, v172, v68
	v_fma_f32 v165, v65, v172, v69
	v_fma_f32 v166, v66, v172, v70
	v_fma_f32 v167, v67, v172, v71
	v_pk_mul_f32 v[176:177], v[184:185], v[176:177]
	v_pk_mul_f32 v[178:179], v[186:187], v[178:179]
	v_pk_mul_f32 v[180:181], v[188:189], v[180:181]
	v_pk_mul_f32 v[182:183], v[190:191], v[182:183]
	v_add_f32_e32 v164, v176, v164
	v_add_f32_e32 v165, v178, v165
	v_add_f32_e32 v166, v180, v166
	v_add_f32_e32 v167, v182, v167
	v_mul_f32_e32 v164, v164, v177
	v_mul_f32_e32 v165, v165, v179
	v_mul_f32_e32 v166, v166, v181
	v_mul_f32_e32 v167, v167, v183
	v_cvt_pk_bf16_f32 v196, v164, v165
	v_cvt_pk_bf16_f32 v197, v166, v167
	global_store_dwordx2 v152, v[196:197], s[12:13]
	s_branch .LBB0_647

.LBB0_647:
	v_add_u32_e32 v23, s80, v130
	v_add_u32_e32 v67, s66, v23
	v_add_u32_e32 v23, s67, v23
	ds_read_b64_tr_b16 v[130:131], v67 offset:0
	ds_read_b64_tr_b16 v[132:133], v67 offset:576
	ds_read_b64_tr_b16 v[112:113], v67 offset:4608
	ds_read_b64_tr_b16 v[114:115], v67 offset:5184
	ds_read_b64_tr_b16 v[100:101], v23 offset:0
	ds_read_b64_tr_b16 v[102:103], v23 offset:576
	ds_read_b64_tr_b16 v[76:77], v23 offset:4608
	ds_read_b64_tr_b16 v[78:79], v23 offset:5184
	ds_read_b64_tr_b16 v[72:73], v23 offset:9216
	ds_read_b64_tr_b16 v[74:75], v23 offset:9792
	ds_read_b64_tr_b16 v[68:69], v23 offset:13824
	ds_read_b64_tr_b16 v[70:71], v23 offset:14400
	s_waitcnt lgkmcnt(0)
	s_and_b64 vcc, exec, s[10:11]
	v_mfma_f32_16x16x32_bf16 v[16:19], v[100:103], v[16:19], 0
	v_mfma_f32_16x16x32_bf16 v[16:19], v[76:79], v[80:83], v[16:19]
	v_mfma_f32_16x16x32_bf16 v[16:19], v[72:75], v[84:87], v[16:19]
	v_mfma_f32_16x16x32_bf16 v[60:63], v[130:133], v[60:63], 0
	v_mfma_f32_16x16x32_bf16 v[16:19], v[68:71], v[96:99], v[16:19]
	v_mfma_f32_16x16x32_bf16 v[56:59], v[112:115], v[56:59], v[60:63]
	s_and_b64 vcc, exec, s[24:25]
	s_cbranch_vccz .Lscan_eB_orig
	s_and_b64 vcc, exec, s[10:11]
	s_cbranch_vccnz .Lscan_eB_ssd
	s_lshl_b64 s[12:13], s[30:31], 1
	s_add_u32 s12, s28, s12
	s_addc_u32 s13, s29, s13
	v_add_u32_e32 v155, s78, v109
	v_lshl_add_u32 v152, v155, 1, v151
	s_nop 3
	v_pk_add_f32 v[196:197], v[16:17], v[56:57]
	v_pk_add_f32 v[198:199], v[18:19], v[58:59]
	v_cvt_pk_bf16_f32 v196, v196, v197
	v_cvt_pk_bf16_f32 v197, v198, v199
	global_store_dwordx2 v152, v[196:197], s[12:13]
	s_branch .LBB0_687
.Lscan_eB_ssd:
	v_mul_u32_u24_e32 v154, s54, v153
	v_add_u32_e32 v155, s78, v109
	v_lshl_add_u32 v154, v155, 1, v154
	v_add_u32_e32 v156, s59, v154
	v_add_u32_e32 v157, s64, v154
	ds_read_b64 v[160:161], v156
	ds_read_b64 v[164:165], v157
	s_lshl_b64 s[12:13], s[34:35], 1
	s_add_u32 s12, s28, s12
	s_addc_u32 s13, s29, s13
	v_lshl_add_u32 v152, v155, 1, v151
	v_mov_b32_e32 v184, v110
	v_mov_b32_e32 v186, v110
	v_mov_b32_e32 v188, v110
	v_mov_b32_e32 v190, v110
	s_waitcnt lgkmcnt(0)
	v_lshlrev_b32_e32 v177, 16, v160
	v_and_b32_e32 v179, 0xffff0000, v160
	v_lshlrev_b32_e32 v181, 16, v161
	v_and_b32_e32 v183, 0xffff0000, v161
	v_mul_f32_e32 v160, 0xbfb8aa3b, v177
	v_mul_f32_e32 v161, 0xbfb8aa3b, v179
	v_mul_f32_e32 v162, 0xbfb8aa3b, v181
	v_mul_f32_e32 v163, 0xbfb8aa3b, v183
	v_exp_f32_e32 v160, v160
	v_exp_f32_e32 v161, v161
	v_exp_f32_e32 v162, v162
	v_exp_f32_e32 v163, v163
	v_lshlrev_b32_e32 v176, 16, v164
	v_and_b32_e32 v178, 0xffff0000, v164
	v_lshlrev_b32_e32 v180, 16, v165
	v_and_b32_e32 v182, 0xffff0000, v165
	v_add_f32_e32 v160, 1.0, v160
	v_add_f32_e32 v161, 1.0, v161
	v_add_f32_e32 v162, 1.0, v162
	v_add_f32_e32 v163, 1.0, v163
	v_rcp_f32_e32 v185, v160
	v_rcp_f32_e32 v187, v161
	v_rcp_f32_e32 v189, v162
	v_rcp_f32_e32 v191, v163
	v_fma_f32 v164, v16, v172, v56
	v_fma_f32 v165, v17, v172, v57
	v_fma_f32 v166, v18, v172, v58
	v_fma_f32 v167, v19, v172, v59
	v_pk_mul_f32 v[176:177], v[184:185], v[176:177]
	v_pk_mul_f32 v[178:179], v[186:187], v[178:179]
	v_pk_mul_f32 v[180:181], v[188:189], v[180:181]
	v_pk_mul_f32 v[182:183], v[190:191], v[182:183]
	v_add_f32_e32 v164, v176, v164
	v_add_f32_e32 v165, v178, v165
	v_add_f32_e32 v166, v180, v166
	v_add_f32_e32 v167, v182, v167
	v_mul_f32_e32 v164, v164, v177
	v_mul_f32_e32 v165, v165, v179
	v_mul_f32_e32 v166, v166, v181
	v_mul_f32_e32 v167, v167, v183
	v_cvt_pk_bf16_f32 v196, v164, v165
	v_cvt_pk_bf16_f32 v197, v166, v167
	global_store_dwordx2 v152, v[196:197], s[12:13]
	s_branch .LBB0_687
